# grid barrier B7 removed: xattn items remapped so each workgroup consumes the Q tile it produced in the preceding GEMM (workgroup-local sync only)
# speedup vs baseline: 1.0742x; 1.0081x over previous
.LBB0_776:
	s_waitcnt vmcnt(0)
	s_and_b64 vcc, exec, s[66:67]
	s_barrier
	s_branch .LBB0_831
.LBB0_831:
	v_readlane_b32 s8, v254, 28
	s_waitcnt lgkmcnt(0)
	s_barrier
	v_mbcnt_lo_u32_b32 v144, -1, 0
	v_mbcnt_hi_u32_b32 v144, -1, v144
	v_readlane_b32 s16, v254, 36
	v_ashrrev_i32_e32 v145, 31, v144
	v_readlane_b32 s17, v254, 37
	v_readlane_b32 s18, v254, 38
	v_readlane_b32 s19, v254, 39
	v_readlane_b32 s20, v254, 40
	v_readlane_b32 s21, v254, 41
	v_lshlrev_b64 v[0:1], 2, v[144:145]
	v_readlane_b32 s22, v254, 42
	v_readlane_b32 s23, v254, 43
	s_mov_b64 s[16:17], s[20:21]
	s_mov_b64 s[18:19], s[22:23]
	v_lshl_add_u64 v[2:3], s[16:17], 0, v[0:1]
	v_lshl_add_u64 v[0:1], s[18:19], 0, v[0:1]
	global_load_dword v4, v[2:3], off
	global_load_dword v5, v[2:3], off offset:256
	global_load_dword v6, v[2:3], off offset:512
	global_load_dword v7, v[2:3], off offset:768
	global_load_dword v8, v[0:1], off
	global_load_dword v9, v[0:1], off offset:256
	global_load_dword v10, v[0:1], off offset:512
	global_load_dword v11, v[0:1], off offset:768
	s_add_u32 s2, s74, 0x6600000
	s_mov_b32 s1, 0
	s_addc_u32 s3, s75, 0
	s_and_b64 vcc, exec, s[4:5]
	v_readlane_b32 s9, v254, 29
	v_readlane_b32 s10, v254, 30
	v_readlane_b32 s11, v254, 31
	v_readlane_b32 s12, v254, 32
	v_readlane_b32 s13, v254, 33
	v_readlane_b32 s14, v254, 34
	v_readlane_b32 s15, v254, 35
	s_waitcnt vmcnt(0)
	v_max3_f32 v0, |v4|, 0, |v5|
	v_mov_b32_e32 v4, 0xc2700000
	v_max3_f32 v0, v0, |v6|, |v7|
	ds_swizzle_b32 v2, v0 offset:swizzle(SWAP,1)
	v_max3_f32 v1, |v8|, 0, |v9|
	v_max3_f32 v1, v1, |v10|, |v11|
	ds_swizzle_b32 v3, v1 offset:swizzle(SWAP,1)
	s_waitcnt lgkmcnt(1)
	v_max_f32_e32 v2, v2, v2
	v_max_f32_e32 v0, v0, v2
	ds_swizzle_b32 v2, v0 offset:swizzle(SWAP,2)
	s_waitcnt lgkmcnt(1)
	v_max_f32_e32 v3, v3, v3
	v_max_f32_e32 v1, v1, v3
	ds_swizzle_b32 v3, v1 offset:swizzle(SWAP,2)
	s_waitcnt lgkmcnt(1)
	v_max_f32_e32 v2, v2, v2
	v_max_f32_e32 v0, v0, v2
	ds_swizzle_b32 v2, v0 offset:swizzle(SWAP,4)
	s_waitcnt lgkmcnt(1)
	v_max_f32_e32 v3, v3, v3
	v_max_f32_e32 v1, v1, v3
	ds_swizzle_b32 v3, v1 offset:swizzle(SWAP,4)
	s_waitcnt lgkmcnt(1)
	v_max_f32_e32 v2, v2, v2
	v_max_f32_e32 v0, v0, v2
	ds_swizzle_b32 v2, v0 offset:swizzle(SWAP,8)
	s_waitcnt lgkmcnt(1)
	v_max_f32_e32 v3, v3, v3
	v_max_f32_e32 v1, v1, v3
	ds_swizzle_b32 v3, v1 offset:swizzle(SWAP,8)
	s_waitcnt lgkmcnt(1)
	v_max_f32_e32 v2, v2, v2
	v_max_f32_e32 v0, v0, v2
	ds_swizzle_b32 v2, v0 offset:swizzle(SWAP,16)
	s_waitcnt lgkmcnt(1)
	v_max_f32_e32 v3, v3, v3
	v_max_f32_e32 v1, v1, v3
	ds_swizzle_b32 v3, v1 offset:swizzle(SWAP,16)
	s_waitcnt lgkmcnt(1)
	v_max_f32_e32 v2, v2, v2
	v_max_f32_e32 v0, v0, v2
	v_mov_b32_e32 v2, v0
	s_nop 1
	v_permlane32_swap_b32_e32 v0, v2
	s_waitcnt lgkmcnt(0)
	v_max_f32_e32 v3, v3, v3
	v_max_f32_e32 v1, v1, v3
	v_mov_b32_e32 v3, v1
	s_nop 1
	v_permlane32_swap_b32_e32 v1, v3
	v_max_f32_e32 v2, v2, v2
	v_max_f32_e32 v0, v0, v0
	v_max_f32_e32 v3, v3, v3
	v_max_f32_e32 v1, v1, v1
	v_max_f32_e32 v0, v0, v2
	v_max_f32_e32 v1, v1, v3
	v_mul_f32_e32 v0, v0, v1
	v_mul_f32_e32 v0, 0x43800000, v0
	v_fmac_f32_e32 v4, 0x3db8aa3b, v0
	v_max_f32_e32 v0, 0, v4
	s_nop 0
	v_readfirstlane_b32 s7, v0
	s_cbranch_vccnz .LBB0_844
	v_readlane_b32 s0, v254, 44
	v_and_b32_e32 v4, 7, v144
	v_readlane_b32 s4, v254, 45
	v_add_u32_e32 v2, s0, v144
	v_lshlrev_b32_e32 v3, 2, v144
	s_add_i32 s0, 0, 0x20000
	v_mov_b32_e32 v149, 0
	v_lshlrev_b32_e32 v148, 4, v4
	v_readlane_b32 s5, v254, 46
	v_readlane_b32 s8, v254, 52
	v_and_b32_e32 v1, 31, v144
	v_add_u32_e32 v161, s0, v3
	v_lshl_add_u64 v[150:151], s[4:5], 0, v[148:149]
	s_add_i32 s0, 0, 0x10000
	s_lshl_b32 s4, s8, 14
	s_add_i32 s4, s0, s4
	v_lshlrev_b32_e32 v7, 9, v1
	v_add_u32_e32 v166, s4, v7
	v_lshlrev_b32_e32 v9, 4, v144
	s_movk_i32 s4, 0x70
	v_ashrrev_i32_e32 v146, 3, v2
	v_bitop3_b32 v2, v2, s4, v9 bitop3:0x48
	v_and_b32_e32 v9, 19, v144
	v_lshlrev_b32_e32 v10, 1, v144
	v_lshrrev_b32_e32 v11, 1, v144
	v_readlane_b32 s5, v254, 48
	v_and_b32_e32 v10, 8, v10
	v_and_or_b32 v9, v11, 4, v9
	s_lshl_b32 s4, s5, 14
	v_or_b32_e32 v12, v9, v10
	s_add_i32 s4, s4, 0
	v_readlane_b32 s6, v254, 25
	v_ashrrev_i32_e32 v145, 5, v144
	v_lshl_add_u32 v168, v12, 9, s4
	s_and_b32 s4, s6, 0x3fffffc
	v_bitop3_b32 v169, v9, 15, v10 bitop3:0xc8
	v_add_u32_e32 v9, s4, v145
	s_lshl_b32 s4, s8, 15
	s_add_i32 s11, s4, 0
	v_lshlrev_b32_e32 v5, 9, v146
	v_add_u32_e32 v171, s11, v3
	v_lshlrev_b32_e32 v3, 3, v145
	v_and_b32_e32 v6, 0x3e00, v5
	v_add3_u32 v172, s11, v7, v3
	v_and_b32_e32 v3, 0xffffc000, v5
	v_add3_u32 v173, s0, v6, v3
	v_bitop3_b32 v3, v146, v4, 15 bitop3:0x6c
	v_lshlrev_b32_e32 v148, 5, v4
	v_lshlrev_b32_e32 v174, 4, v3
	v_or_b32_e32 v3, 8, v4
	v_lshl_add_u64 v[152:153], s[16:17], 0, v[148:149]
	v_lshlrev_b32_e32 v148, 5, v3
	v_bitop3_b32 v3, v146, v3, 15 bitop3:0x6c
	v_lshlrev_b32_e32 v175, 4, v3
	v_or_b32_e32 v3, 16, v4
	v_lshl_add_u64 v[154:155], s[16:17], 0, v[148:149]
	v_lshlrev_b32_e32 v148, 5, v3
	v_bitop3_b32 v3, v146, v3, 15 bitop3:0x6c
	v_lshlrev_b32_e32 v176, 4, v3
	v_or_b32_e32 v3, 24, v4
	v_lshlrev_b32_e32 v0, 3, v4
	v_lshl_add_u64 v[156:157], s[16:17], 0, v[148:149]
	v_lshlrev_b32_e32 v148, 5, v3
	v_bitop3_b32 v3, v146, v3, 15 bitop3:0x6c
	v_add_u32_e32 v4, 2, v9
	v_lshlrev_b32_e32 v177, 4, v3
	v_bitop3_b32 v3, v9, v11, 7 bitop3:0x78
	v_bitop3_b32 v4, v4, v11, 7 bitop3:0x78
	v_lshlrev_b32_e32 v178, 4, v1
	v_add_u32_e32 v167, 0, v5
	v_lshl_add_u32 v8, v146, 7, 0
	v_lshl_add_u32 v10, v1, 7, 0
	s_cmp_eq_u32 s5, 1
	v_lshlrev_b32_e32 v3, 4, v3
	v_lshlrev_b32_e32 v4, 4, v4
	v_xor_b32_e32 v1, 16, v178
	v_xor_b32_e32 v5, 32, v178
	v_xor_b32_e32 v6, 48, v178
	v_xor_b32_e32 v7, 64, v178
	v_xor_b32_e32 v9, 0x50, v178
	v_xor_b32_e32 v11, 0x60, v178
	v_xor_b32_e32 v12, 0x70, v178
	v_xor_b32_e32 v13, 0x80, v178
	v_xor_b32_e32 v14, 0x90, v178
	v_xor_b32_e32 v15, 0xa0, v178
	v_xor_b32_e32 v16, 0xb0, v178
	v_xor_b32_e32 v17, 0xc0, v178
	v_xor_b32_e32 v18, 0xd0, v178
	v_xor_b32_e32 v19, 0xe0, v178
	v_xor_b32_e32 v20, 0xf0, v178
	v_xor_b32_e32 v21, 0x100, v178
	v_xor_b32_e32 v22, 0x110, v178
	v_xor_b32_e32 v23, 0x120, v178
	v_xor_b32_e32 v24, 0x130, v178
	v_xor_b32_e32 v25, 0x140, v178
	v_xor_b32_e32 v26, 0x150, v178
	v_xor_b32_e32 v27, 0x160, v178
	v_xor_b32_e32 v28, 0x170, v178
	v_xor_b32_e32 v29, 0x180, v178
	v_xor_b32_e32 v30, 0x190, v178
	v_xor_b32_e32 v31, 0x1a0, v178
	v_xor_b32_e32 v32, 0x1b0, v178
	v_xor_b32_e32 v33, 0x1c0, v178
	v_xor_b32_e32 v34, 0x1d0, v178
	v_xor_b32_e32 v35, 0x1e0, v178
	v_xor_b32_e32 v36, 0x1f0, v178
	s_mov_b32 s10, 0x20000
	v_ashrrev_i32_e32 v147, 31, v146
	v_and_b32_e32 v170, 15, v144
	s_cselect_b64 s[4:5], -1, 0
	s_lshl_b32 s12, s8, 8
	s_lshl_b32 s13, s6, 8
	v_lshl_add_u64 v[158:159], s[16:17], 0, v[148:149]
	s_mov_b32 s6, 0x3b800000
	s_mov_b32 s14, 0x800000
	v_lshlrev_b32_e32 v148, 1, v0
	v_add_u32_e32 v179, v8, v2
	v_add_u32_e32 v180, v10, v3
	v_add_u32_e32 v181, v10, v4
	v_add_u32_e32 v182, v172, v1
	v_add_u32_e32 v183, v172, v5
	v_add_u32_e32 v184, v172, v6
	v_add_u32_e32 v185, v172, v7
	v_add_u32_e32 v186, v172, v9
	v_add_u32_e32 v187, v172, v11
	v_add_u32_e32 v188, v172, v12
	v_add_u32_e32 v189, v172, v13
	v_add_u32_e32 v190, v172, v14
	v_add_u32_e32 v191, v172, v15
	v_add_u32_e32 v192, v172, v16
	v_add_u32_e32 v193, v172, v17
	v_add_u32_e32 v194, v172, v18
	v_add_u32_e32 v195, v172, v19
	v_add_u32_e32 v196, v172, v20
	v_add_u32_e32 v197, v172, v21
	v_add_u32_e32 v198, v172, v22
	v_add_u32_e32 v199, v172, v23
	v_add_u32_e32 v200, v172, v24
	v_add_u32_e32 v201, v172, v25
	v_add_u32_e32 v202, v172, v26
	v_add_u32_e32 v203, v172, v27
	v_add_u32_e32 v204, v172, v28
	v_add_u32_e32 v205, v172, v29
	v_add_u32_e32 v206, v172, v30
	v_add_u32_e32 v207, v172, v31
	v_add_u32_e32 v208, v172, v32
	v_add_u32_e32 v209, v172, v33
	v_add_u32_e32 v210, v172, v34
	v_add_u32_e32 v211, v172, v35
	v_add_u32_e32 v212, v172, v36
	v_mov_b32_e32 v160, 0x358637bd
	s_and_b32 s15, s70, 7
	s_lshr_b32 s98, s15, 2
	s_lshl_b32 s98, s98, 8
	s_and_b32 s15, s15, 3
	s_lshl_b32 s15, s15, 4
	s_or_b32 s15, s15, s98
	s_lshr_b32 s98, s70, 3
	s_and_b32 s98, s98, 7
	s_lshl_b32 s98, s98, 1
	s_or_b32 s15, s15, s98
	s_lshr_b32 s98, s70, 6
	s_lshl_b32 s98, s98, 6
	s_or_b32 s15, s15, s98
	s_branch .LBB0_834
.LBB0_833:
	s_add_i32 s15, s15, 1
	s_bitcmp1_b32 s15, 0
	s_cbranch_scc0 .LBB0_844

	.amdhsa_kernel _Z9hymba_fwd6Params
		.amdhsa_group_segment_fixed_size 0
		.amdhsa_private_segment_fixed_size 0
		.amdhsa_kernarg_size 448
		.amdhsa_user_sgpr_count 2
		.amdhsa_user_sgpr_dispatch_ptr 0
		.amdhsa_user_sgpr_queue_ptr 0
		.amdhsa_user_sgpr_kernarg_segment_ptr 1
		.amdhsa_user_sgpr_dispatch_id 0
		.amdhsa_user_sgpr_kernarg_preload_length 0
		.amdhsa_user_sgpr_kernarg_preload_offset 0
		.amdhsa_user_sgpr_private_segment_size 0
		.amdhsa_uses_dynamic_stack 0
		.amdhsa_enable_private_segment 0
		.amdhsa_system_sgpr_workgroup_id_x 1
		.amdhsa_system_sgpr_workgroup_id_y 0
		.amdhsa_system_sgpr_workgroup_id_z 0
		.amdhsa_system_sgpr_workgroup_info 0
		.amdhsa_system_vgpr_workitem_id 2
		.amdhsa_next_free_vgpr 256
		.amdhsa_next_free_sgpr 102
		.amdhsa_accum_offset 256
		.amdhsa_reserve_vcc 1
		.amdhsa_float_round_mode_32 0
		.amdhsa_float_round_mode_16_64 0
		.amdhsa_float_denorm_mode_32 3
		.amdhsa_float_denorm_mode_16_64 3
		.amdhsa_dx10_clamp 1
		.amdhsa_ieee_mode 1
		.amdhsa_fp16_overflow 0
		.amdhsa_tg_split 0
		.amdhsa_exception_fp_ieee_invalid_op 0
		.amdhsa_exception_fp_denorm_src 0
		.amdhsa_exception_fp_ieee_div_zero 0
		.amdhsa_exception_fp_ieee_overflow 0
		.amdhsa_exception_fp_ieee_underflow 0
		.amdhsa_exception_fp_ieee_inexact 0
		.amdhsa_exception_int_div_zero 0
	.end_amdhsa_kernel

amdhsa.kernels:
  - .agpr_count:     0
    .args:
      - .offset:         0
        .size:           192
        .value_kind:     by_value
      - .offset:         192
        .size:           4
        .value_kind:     hidden_block_count_x
      - .offset:         196
        .size:           4
        .value_kind:     hidden_block_count_y
      - .offset:         200
        .size:           4
        .value_kind:     hidden_block_count_z
      - .offset:         204
        .size:           2
        .value_kind:     hidden_group_size_x
      - .offset:         206
        .size:           2
        .value_kind:     hidden_group_size_y
      - .offset:         208
        .size:           2
        .value_kind:     hidden_group_size_z
      - .offset:         210
        .size:           2
        .value_kind:     hidden_remainder_x
      - .offset:         212
        .size:           2
        .value_kind:     hidden_remainder_y
      - .offset:         214
        .size:           2
        .value_kind:     hidden_remainder_z
      - .offset:         232
        .size:           8
        .value_kind:     hidden_global_offset_x
      - .offset:         240
        .size:           8
        .value_kind:     hidden_global_offset_y
      - .offset:         248
        .size:           8
        .value_kind:     hidden_global_offset_z
      - .offset:         256
        .size:           2
        .value_kind:     hidden_grid_dims
      - .offset:         280
        .size:           8
        .value_kind:     hidden_multigrid_sync_arg
      - .offset:         312
        .size:           4
        .value_kind:     hidden_dynamic_lds_size
    .group_segment_fixed_size: 0
    .kernarg_segment_align: 8
    .kernarg_segment_size: 448
    .language:       OpenCL C
    .language_version:
      - 2
      - 0
    .max_flat_workgroup_size: 512
    .name:           _Z9hymba_fwd6Params
    .private_segment_fixed_size: 0
    .sgpr_count:     108
    .sgpr_spill_count: 98
    .symbol:         _Z9hymba_fwd6Params.kd
    .uniform_work_group_size: 1
    .uses_dynamic_stack: false
    .vgpr_count:     256
    .vgpr_spill_count: 0
    .wavefront_size: 64
